# grid barrier: the globally last XCD leader bumps every XCD's release word itself (no per-XCD relay hop); other leaders no longer add
# baseline (speedup 1.0000x reference)
; __device__ __forceinline__ unsigned xb_ld(unsigned* p)              { return __hip_atomic_load(p, __ATOMIC_RELAXED, __HIP_MEMORY_SCOPE_AGENT); }
; __device__ __forceinline__ unsigned xb_add(unsigned* p, unsigned v) { return __hip_atomic_fetch_add(p, v, __ATOMIC_RELAXED, __HIP_MEMORY_SCOPE_AGENT); }
; #define XB_SPIN(cond, bar) do { unsigned _sp = 0; while (cond) { __builtin_amdgcn_s_sleep(1); \
;     if ((++_sp & 255u) == 0u) { if (xb_ld(&(bar)[XB_TMO])) break; if (_sp > XB_SPIN_CAP) { atomicAdd(&(bar)[XB_TMO], 1u); break; } } } } while (0)
; __device__ __forceinline__ void xcd_barrier(const XcdBarrier& b) {
;     ...
;             const unsigned og = xb_add(&bar[XB_TOP], 1u);
;             const unsigned tg = og / nx;
;             if (og + 1u == (tg + 1u) * nx) xb_add(&bar[XB_TOPGEN], 1u);
;             else XB_SPIN(xb_ld(&bar[XB_TOPGEN]) == tg, bar);
.LBB0_80:
	s_or_b64 exec, exec, s[8:9]
	v_cvt_f32_u32_e32 v3, v0
	s_waitcnt vmcnt(0)
	v_readfirstlane_b32 s6, v2
	s_add_u32 s8, s92, 0x1ef03500
	s_addc_u32 s9, s93, 0
	v_rcp_iflag_f32_e32 v3, v3
	v_add_u32_e32 v1, s6, v1
	v_add_u32_e32 v4, 1, v1
	s_mov_b64 s[10:11], -1
	v_mul_f32_e32 v2, 0x4f7ffffe, v3
	v_cvt_u32_f32_e32 v2, v2
	v_sub_u32_e32 v3, 0, v0
	v_mul_lo_u32 v3, v3, v2
	v_mul_hi_u32 v3, v2, v3
	v_add_u32_e32 v2, v2, v3
	v_mul_hi_u32 v2, v1, v2
	v_mul_lo_u32 v3, v2, v0
	v_sub_u32_e32 v1, v1, v3
	v_add_u32_e32 v5, 1, v2
	v_cmp_ge_u32_e32 vcc, v1, v0
	v_sub_u32_e32 v3, v1, v0
	s_nop 0
	v_cndmask_b32_e32 v2, v2, v5, vcc
	v_cndmask_b32_e32 v1, v1, v3, vcc
	v_add_u32_e32 v3, 1, v2
	v_cmp_ge_u32_e32 vcc, v1, v0
	s_nop 1
	v_cndmask_b32_e32 v2, v2, v3, vcc
	v_mul_lo_u32 v1, v0, v2
	v_add_u32_e32 v0, v1, v0
	v_cmp_ne_u32_e32 vcc, v4, v0
	v_mov_b64_e32 v[0:1], s[8:9]
	s_mov_b64 s[98:99], vcc
	s_and_saveexec_b64 s[6:7], vcc
	s_cbranch_execz .LBB0_92
	v_mov_b32_e32 v0, 0
	global_load_dword v1, v0, s[8:9] sc1
	s_mov_b64 s[14:15], 0
	s_waitcnt vmcnt(0)
	v_cmp_eq_u32_e32 vcc, v1, v2
	s_and_saveexec_b64 s[12:13], vcc
	s_cbranch_execz .LBB0_91
	s_add_u32 s10, s92, 0x1ef00200
	s_addc_u32 s11, s93, 0
	s_mov_b32 s24, 1
	s_branch .LBB0_84

; __device__ __forceinline__ unsigned xb_add(unsigned* p, unsigned v) { return __hip_atomic_fetch_add(p, v, __ATOMIC_RELAXED, __HIP_MEMORY_SCOPE_AGENT); }
; __device__ __forceinline__ void xcd_barrier(const XcdBarrier& b) {
;     ...
;             __builtin_amdgcn_fence(__ATOMIC_ACQUIRE, "agent");
;             xb_add(&bar[XB_XGEN(b.x)], 1u);
;             asm volatile("s_waitcnt vmcnt(0)" ::: "memory");
.LBB0_94:
	s_or_b64 exec, exec, s[6:7]
	s_mov_b64 s[6:7], exec
	v_mbcnt_lo_u32_b32 v0, s6, 0
	v_mbcnt_hi_u32_b32 v0, s7, v0
	v_cmp_eq_u32_e32 vcc, 0, v0
	s_waitcnt vmcnt(0)
	s_and_saveexec_b64 s[8:9], vcc
	s_cbranch_execz .LBB0_96
	s_bcnt1_i32_b64 s6, s[6:7]
	s_cmp_eq_u64 s[98:99], 0
	s_cbranch_scc0 .Lxgrel_0
	v_mov_b32_e32 v1, 1
	v_mov_b32_e32 v0, 0x1ef02400
	global_atomic_add v0, v1, s[92:93]
	v_add_u32_e32 v0, 0x100, v0
	global_atomic_add v0, v1, s[92:93]
	v_add_u32_e32 v0, 0x100, v0
	global_atomic_add v0, v1, s[92:93]
	v_add_u32_e32 v0, 0x100, v0
	global_atomic_add v0, v1, s[92:93]
	v_add_u32_e32 v0, 0x100, v0
	global_atomic_add v0, v1, s[92:93]
	v_add_u32_e32 v0, 0x100, v0
	global_atomic_add v0, v1, s[92:93]
	v_add_u32_e32 v0, 0x100, v0
	global_atomic_add v0, v1, s[92:93]
	v_add_u32_e32 v0, 0x100, v0
	global_atomic_add v0, v1, s[92:93]
	v_add_u32_e32 v0, 0x100, v0
	global_atomic_add v0, v1, s[92:93]
	v_add_u32_e32 v0, 0x100, v0
	global_atomic_add v0, v1, s[92:93]
	v_add_u32_e32 v0, 0x100, v0
	global_atomic_add v0, v1, s[92:93]
	v_add_u32_e32 v0, 0x100, v0
	global_atomic_add v0, v1, s[92:93]
	v_add_u32_e32 v0, 0x100, v0
	global_atomic_add v0, v1, s[92:93]
	v_add_u32_e32 v0, 0x100, v0
	global_atomic_add v0, v1, s[92:93]
	v_add_u32_e32 v0, 0x100, v0
	global_atomic_add v0, v1, s[92:93]
	v_add_u32_e32 v0, 0x100, v0
	global_atomic_add v0, v1, s[92:93]
.Lxgrel_0:
.LBB0_96:
	s_or_b64 exec, exec, s[8:9]
	s_waitcnt vmcnt(0)
